# mixers phase: odd workgroups process their six units in reverse order (compute-heavy and memory-bound units overlap chip-wide)
# baseline (speedup 1.0000x reference)
.LBB0_368:
	v_readlane_b32 s8, v254, 0
	v_readlane_b32 s9, v254, 1
	v_readlane_b32 s10, v254, 2
	v_readlane_b32 s11, v254, 3
	s_mov_b32 s6, s90
	s_mov_b64 s[4:5], s[10:11]
	s_mov_b64 s[36:37], s[8:9]
	s_waitcnt lgkmcnt(0)
	s_barrier
	v_mov_b32 v0, 0
	v_readlane_b32 s0, v254, 30
	v_mbcnt_lo_u32_b32 v0, -1, v0
	v_mbcnt_hi_u32_b32 v0, -1, v0
	v_readlane_b32 s1, v254, 31
	v_writelane_b32 v255, s96, 24
	v_lshl_or_b32 v151, s6, 6, v0
	s_andn2_b64 vcc, exec, s[0:1]
	v_writelane_b32 v255, s97, 25
	v_readlane_b32 s12, v254, 4
	v_readlane_b32 s13, v254, 5
	v_readlane_b32 s14, v254, 6
	v_readlane_b32 s15, v254, 7
	v_readlane_b32 s16, v254, 8
	v_readlane_b32 s17, v254, 9
	v_readlane_b32 s18, v254, 10
	v_readlane_b32 s19, v254, 11
	v_readlane_b32 s20, v254, 12
	v_readlane_b32 s21, v254, 13
	v_readlane_b32 s22, v254, 14
	v_readlane_b32 s23, v254, 15
	s_cbranch_vccnz .LBB0_470
	s_cmp_eq_u32 s96, 2
	s_cselect_b64 vcc, -1, 0
	s_lshl_b64 s[0:1], s[96:97], 9
	v_writelane_b32 v255, s0, 26
	v_mov_b32_e32 v0, 0x3f0e59d5
	v_mov_b32_e32 v1, 0x3ef1014c
	v_writelane_b32 v255, s1, 27
	v_writelane_b32 v255, s76, 28
	v_readlane_b32 s0, v254, 54
	v_writelane_b32 v255, s36, 29
	v_cndmask_b32_e32 v166, v0, v1, vcc
	v_readlane_b32 s34, v254, 56
	s_mov_b32 s35, s0
	s_bitcmp1_b32 s0, 0
	s_cselect_b32 s1, 0x500, 0
	s_add_i32 s35, s35, s1
	s_add_i32 s34, s34, s1
	v_writelane_b32 v255, s37, 30
	s_nop 0
	v_readlane_b32 s1, v254, 55
	s_branch .LBB0_372

.LBB0_371:
	v_readlane_b32 s4, v254, 54
	s_nop 1
	s_bitcmp1_b32 s4, 0
	s_cselect_b32 s4, -1, 1
	s_lshl_b32 s4, s4, 8
	s_add_i32 s35, s35, s4
	s_add_i32 s34, s34, s4
	s_cmpk_lt_u32 s35, 0x600
	s_cbranch_scc0 .LBB0_470
